# s5_scan loads one 16-chunk trip ahead (two register sets); S5 K-fold GEMM dealt to workgroups 64..127 so scan workgroups own no fold unit
# speedup vs baseline: 1.0100x; 1.0034x over previous
; DEVI int otid() { int t = threadIdx.x; asm volatile("" : "+v"(t)); return t; }
; DEVI int obid() { int t = blockIdx.x; asm volatile("" : "+s"(t)); return t; }
; DEVI u16 f2bf(float f) { return (u16)(cvt_pk(f, 0.f) & 0xffffu); }
; DEVI void s5_scan(const Params& p) {
;     const float* apow = (const float*)(p.ws + OFF_APOW); const float* send = (const float*)(p.ws + OFF_SEND); u16* ue = (u16*)(p.ws + OFF_UEXT);
;     for (int e = obid() * 512 + otid(); e < 64 * 4 * 64; e += gridDim.x * 512) { const int pp = e & 63, b = (e >> 6) & 3, g = e >> 8;
;         const float ar = apow[(((size_t)g * 64 + pp) * 34 + 32) * 2], ai = apow[(((size_t)g * 64 + pp) * 34 + 32) * 2 + 1]; float rr = 0.f, ri = 0.f;
; #pragma unroll 16
;         for (int c = 0; c < 256; ++c) { const size_t row = (size_t)g * 1024 + b * 256 + c; const float er = send[row * 128 + pp], ei = send[row * 128 + 64 + pp];
;             ue[row * 640 + 512 + pp] = f2bf(rr); ue[row * 640 + 576 + pp] = f2bf(ri);
;             const float nr = ar * rr - ai * ri + er, ni = ar * ri + ai * rr + ei; rr = nr; ri = ni; } }
.LBB0_1184:
	v_ashrrev_i32_e32 v14, 8, v1
	v_lshl_or_b32 v8, v14, 6, v0
	v_mov_b64_e32 v[6:7], s[56:57]
	v_mad_i64_i32 v[6:7], s[0:1], v8, s52, v[6:7]
	global_load_dwordx2 v[6:7], v[6:7], off offset:256
	v_mul_i32_i24_e32 v8, 0x140000, v14
	v_ashrrev_i32_e32 v15, 31, v14
	v_mul_hi_i32_i24_e32 v13, 0x140000, v14
	v_or_b32_e32 v12, v2, v8
	v_bfe_u32 v8, v3, 8, 2
	s_mov_b32 s0, 0x50000
	v_mad_u64_u32 v[12:13], s[0:1], v8, s0, v[12:13]
	v_lshlrev_b64 v[14:15], 19, v[14:15]
	v_lshlrev_b32_e32 v5, 9, v3
	v_or_b32_e32 v8, v4, v14
	s_mov_b32 s0, 0x60000
	v_mov_b32_e32 v16, 0
	v_and_or_b32 v14, v5, s0, v8
	s_movk_i32 s6, 0x100
	v_mov_b32_e32 v17, v16
	s_waitcnt vmcnt(0)
	v_pk_mov_b32 v[10:11], v[6:7], v[6:7] op_sel:[1,0]
	v_lshl_add_u64 v[20:21], s[20:21], 0, v[14:15]
	v_add_co_u32_e32 v22, vcc, 0x12380000, v20
	s_nop 1
	v_addc_co_u32_e32 v23, vcc, 0, v21, vcc
	s_mov_b32 s0, 0x12381000
	v_add_co_u32_e32 v20, vcc, s0, v20
	s_nop 1
	v_addc_co_u32_e32 v21, vcc, 0, v21, vcc
	global_load_dword v60, v[22:23], off
	global_load_dword v61, v[22:23], off offset:256
	global_load_dword v62, v[22:23], off offset:512
	global_load_dword v63, v[22:23], off offset:768
	global_load_dword v64, v[22:23], off offset:1024
	global_load_dword v65, v[22:23], off offset:1280
	global_load_dword v66, v[22:23], off offset:1536
	global_load_dword v67, v[22:23], off offset:1792
	global_load_dword v68, v[22:23], off offset:2048
	global_load_dword v69, v[22:23], off offset:2304
	global_load_dword v70, v[22:23], off offset:2560
	global_load_dword v71, v[22:23], off offset:2816
	global_load_dword v72, v[22:23], off offset:3072
	global_load_dword v73, v[22:23], off offset:3328
	global_load_dword v74, v[22:23], off offset:3584
	global_load_dword v75, v[22:23], off offset:3840
	global_load_dword v126, v[20:21], off
	global_load_dword v127, v[20:21], off offset:256
	global_load_dword v128, v[20:21], off offset:512
	global_load_dword v129, v[20:21], off offset:768
	global_load_dword v130, v[20:21], off offset:1024
	global_load_dword v131, v[20:21], off offset:1280
	global_load_dword v132, v[20:21], off offset:1536
	global_load_dword v133, v[20:21], off offset:1792
	global_load_dword v134, v[20:21], off offset:2048
	global_load_dword v135, v[20:21], off offset:2304
	global_load_dword v136, v[20:21], off offset:2560
	global_load_dword v137, v[20:21], off offset:2816
	global_load_dword v138, v[20:21], off offset:3072
	global_load_dword v139, v[20:21], off offset:3328
	global_load_dword v140, v[20:21], off offset:3584
	global_load_dword v141, v[20:21], off offset:3840
	v_lshl_add_u64 v[14:15], v[14:15], 0, s[74:75]
	s_waitcnt vmcnt(0)
.LBB0_1185:
	s_waitcnt vmcnt(30)
	v_lshl_add_u64 v[20:21], s[20:21], 0, v[14:15]
	v_add_co_u32_e32 v22, vcc, 0x12380000, v20
	s_nop 1
	v_addc_co_u32_e32 v23, vcc, 0, v21, vcc
	s_mov_b32 s0, 0x12381000
	v_add_co_u32_e32 v20, vcc, s0, v20
	s_nop 1
	v_addc_co_u32_e32 v21, vcc, 0, v21, vcc
	global_load_dword v214, v[22:23], off
	global_load_dword v215, v[22:23], off offset:256
	global_load_dword v216, v[22:23], off offset:512
	global_load_dword v217, v[22:23], off offset:768
	global_load_dword v218, v[22:23], off offset:1024
	global_load_dword v219, v[22:23], off offset:1280
	global_load_dword v220, v[22:23], off offset:1536
	global_load_dword v221, v[22:23], off offset:1792
	global_load_dword v222, v[22:23], off offset:2048
	global_load_dword v223, v[22:23], off offset:2304
	global_load_dword v224, v[22:23], off offset:2560
	global_load_dword v225, v[22:23], off offset:2816
	global_load_dword v226, v[22:23], off offset:3072
	global_load_dword v227, v[22:23], off offset:3328
	global_load_dword v228, v[22:23], off offset:3584
	global_load_dword v229, v[22:23], off offset:3840
	global_load_dword v230, v[20:21], off
	global_load_dword v231, v[20:21], off offset:256
	global_load_dword v232, v[20:21], off offset:512
	global_load_dword v233, v[20:21], off offset:768
	global_load_dword v234, v[20:21], off offset:1024
	global_load_dword v235, v[20:21], off offset:1280
	global_load_dword v236, v[20:21], off offset:1536
	global_load_dword v237, v[20:21], off offset:1792
	global_load_dword v238, v[20:21], off offset:2048
	global_load_dword v239, v[20:21], off offset:2304
	global_load_dword v244, v[20:21], off offset:2560
	global_load_dword v245, v[20:21], off offset:2816
	global_load_dword v246, v[20:21], off offset:3072
	global_load_dword v247, v[20:21], off offset:3328
	global_load_dword v248, v[20:21], off offset:3584
	global_load_dword v249, v[20:21], off offset:3840
	v_lshl_add_u64 v[14:15], v[14:15], 0, s[74:75]
	v_lshl_add_u64 v[18:19], s[20:21], 0, v[12:13]
	s_mov_b32 s0, 0xd380000
	v_add_co_u32_e32 v142, vcc, s0, v18
	s_nop 1
	v_addc_co_u32_e32 v143, vcc, 0, v19, vcc
	s_mov_b32 s0, 0xd381000
	v_add_co_u32_e32 v144, vcc, s0, v18
	s_nop 1
	v_addc_co_u32_e32 v145, vcc, 0, v19, vcc
	s_mov_b32 s0, 0xd382000
	v_add_co_u32_e32 v146, vcc, s0, v18
	s_nop 1
	v_addc_co_u32_e32 v147, vcc, 0, v19, vcc
	s_mov_b32 s0, 0xd383000
	v_add_co_u32_e32 v148, vcc, s0, v18
	s_nop 1
	v_addc_co_u32_e32 v149, vcc, 0, v19, vcc
	s_mov_b32 s0, 0xd384000
	v_add_co_u32_e32 v150, vcc, s0, v18
	s_nop 1
	v_addc_co_u32_e32 v151, vcc, 0, v19, vcc
	s_mov_b64 s[0:1], 0x5000
	v_lshl_add_u64 v[12:13], v[12:13], 0, s[0:1]
	v_cvt_pk_bf16_f32 v5, v16, s0
	v_pk_mul_f32 v[28:29], v[10:11], v[16:17] op_sel:[0,1]
	s_waitcnt vmcnt(61)
	global_store_short v[142:143], v5, off offset:1024
	v_cvt_pk_bf16_f32 v5, v17, s0
	v_pk_fma_f32 v[30:31], v[6:7], v[16:17], v[28:29] neg_lo:[0,0,1] neg_hi:[0,0,1]
	v_pk_fma_f32 v[16:17], v[6:7], v[16:17], v[28:29] op_sel_hi:[1,0,1]
	global_store_short v[142:143], v5, off offset:1152
	v_mov_b32_e32 v31, v17
	s_nop 0
	v_pk_add_f32 v[16:17], v[30:31], v[60:61]
	s_nop 0
	v_cvt_pk_bf16_f32 v5, v16, s0
	v_pk_mul_f32 v[28:29], v[10:11], v[16:17] op_sel:[0,1]
	s_waitcnt vmcnt(61)
; DEVI u16 f2bf(float f) { return (u16)(cvt_pk(f, 0.f) & 0xffffu); }
; DEVI void s5_scan(const Params& p) {
;     ...
; #pragma unroll 16
;         for (int c = 0; c < 256; ++c) { const size_t row = (size_t)g * 1024 + b * 256 + c; const float er = send[row * 128 + pp], ei = send[row * 128 + 64 + pp];
;             ue[row * 640 + 512 + pp] = f2bf(rr); ue[row * 640 + 576 + pp] = f2bf(ri);
;             const float nr = ar * rr - ai * ri + er, ni = ar * ri + ai * rr + ei; rr = nr; ri = ni; } }
	global_store_short v[142:143], v5, off offset:2304
	v_cvt_pk_bf16_f32 v5, v17, s0
	v_pk_fma_f32 v[30:31], v[6:7], v[16:17], v[28:29] neg_lo:[0,0,1] neg_hi:[0,0,1]
	v_pk_fma_f32 v[16:17], v[6:7], v[16:17], v[28:29] op_sel_hi:[1,0,1]
	global_store_short v[142:143], v5, off offset:2432
	v_mov_b32_e32 v31, v17
	s_nop 0
	v_pk_add_f32 v[16:17], v[30:31], v[62:63]
	s_nop 0
	v_cvt_pk_bf16_f32 v5, v16, s0
	v_pk_mul_f32 v[28:29], v[10:11], v[16:17] op_sel:[0,1]
	s_waitcnt vmcnt(61)
	global_store_short v[142:143], v5, off offset:3584
	v_cvt_pk_bf16_f32 v5, v17, s0
	v_pk_fma_f32 v[30:31], v[6:7], v[16:17], v[28:29] neg_lo:[0,0,1] neg_hi:[0,0,1]
	v_pk_fma_f32 v[16:17], v[6:7], v[16:17], v[28:29] op_sel_hi:[1,0,1]
	global_store_short v[142:143], v5, off offset:3712
	v_mov_b32_e32 v31, v17
	s_nop 0
	v_pk_add_f32 v[16:17], v[30:31], v[64:65]
	s_nop 0
	v_cvt_pk_bf16_f32 v5, v16, s0
	v_pk_mul_f32 v[28:29], v[10:11], v[16:17] op_sel:[0,1]
	s_waitcnt vmcnt(61)
	global_store_short v[144:145], v5, off offset:768
	v_cvt_pk_bf16_f32 v5, v17, s0
	v_pk_fma_f32 v[30:31], v[6:7], v[16:17], v[28:29] neg_lo:[0,0,1] neg_hi:[0,0,1]
	v_pk_fma_f32 v[16:17], v[6:7], v[16:17], v[28:29] op_sel_hi:[1,0,1]
	global_store_short v[144:145], v5, off offset:896
	v_mov_b32_e32 v31, v17
	s_nop 0
	v_pk_add_f32 v[16:17], v[30:31], v[66:67]
	s_nop 0
	v_cvt_pk_bf16_f32 v5, v16, s0
	v_pk_mul_f32 v[28:29], v[10:11], v[16:17] op_sel:[0,1]
	s_waitcnt vmcnt(61)
	global_store_short v[144:145], v5, off offset:2048
	v_cvt_pk_bf16_f32 v5, v17, s0
	v_pk_fma_f32 v[30:31], v[6:7], v[16:17], v[28:29] neg_lo:[0,0,1] neg_hi:[0,0,1]
	v_pk_fma_f32 v[16:17], v[6:7], v[16:17], v[28:29] op_sel_hi:[1,0,1]
	global_store_short v[144:145], v5, off offset:2176
	v_mov_b32_e32 v31, v17
	s_nop 0
	v_pk_add_f32 v[16:17], v[30:31], v[68:69]
	s_nop 0
	v_cvt_pk_bf16_f32 v5, v16, s0
	v_pk_mul_f32 v[28:29], v[10:11], v[16:17] op_sel:[0,1]
	s_waitcnt vmcnt(61)
	global_store_short v[144:145], v5, off offset:3328
	v_cvt_pk_bf16_f32 v5, v17, s0
	v_pk_fma_f32 v[30:31], v[6:7], v[16:17], v[28:29] neg_lo:[0,0,1] neg_hi:[0,0,1]
	v_pk_fma_f32 v[16:17], v[6:7], v[16:17], v[28:29] op_sel_hi:[1,0,1]
	global_store_short v[144:145], v5, off offset:3456
	v_mov_b32_e32 v31, v17
	s_nop 0
	v_pk_add_f32 v[16:17], v[30:31], v[70:71]
	s_nop 0
	v_cvt_pk_bf16_f32 v5, v16, s0
	v_pk_mul_f32 v[28:29], v[10:11], v[16:17] op_sel:[0,1]
	s_waitcnt vmcnt(61)
	global_store_short v[146:147], v5, off offset:512
	v_cvt_pk_bf16_f32 v5, v17, s0
	v_pk_fma_f32 v[30:31], v[6:7], v[16:17], v[28:29] neg_lo:[0,0,1] neg_hi:[0,0,1]
	v_pk_fma_f32 v[16:17], v[6:7], v[16:17], v[28:29] op_sel_hi:[1,0,1]
	global_store_short v[146:147], v5, off offset:640
	v_mov_b32_e32 v31, v17
	s_nop 0
	v_pk_add_f32 v[16:17], v[30:31], v[72:73]
	s_nop 0
	v_cvt_pk_bf16_f32 v5, v16, s0
	v_pk_mul_f32 v[28:29], v[10:11], v[16:17] op_sel:[0,1]
	s_waitcnt vmcnt(61)
	global_store_short v[146:147], v5, off offset:1792
	v_cvt_pk_bf16_f32 v5, v17, s0
	v_pk_fma_f32 v[30:31], v[6:7], v[16:17], v[28:29] neg_lo:[0,0,1] neg_hi:[0,0,1]
	v_pk_fma_f32 v[16:17], v[6:7], v[16:17], v[28:29] op_sel_hi:[1,0,1]
	global_store_short v[146:147], v5, off offset:1920
	v_mov_b32_e32 v31, v17
	s_nop 0
	v_pk_add_f32 v[16:17], v[30:31], v[74:75]
	s_nop 0
	v_cvt_pk_bf16_f32 v5, v16, s0
	v_pk_mul_f32 v[28:29], v[10:11], v[16:17] op_sel:[0,1]
	s_waitcnt vmcnt(61)
	global_store_short v[146:147], v5, off offset:3072
	v_cvt_pk_bf16_f32 v5, v17, s0
	v_pk_fma_f32 v[30:31], v[6:7], v[16:17], v[28:29] neg_lo:[0,0,1] neg_hi:[0,0,1]
	v_pk_fma_f32 v[16:17], v[6:7], v[16:17], v[28:29] op_sel_hi:[1,0,1]
	global_store_short v[146:147], v5, off offset:3200
	v_mov_b32_e32 v31, v17
	s_nop 0
	v_pk_add_f32 v[16:17], v[30:31], v[126:127]
	s_nop 0
	v_cvt_pk_bf16_f32 v5, v16, s0
	v_pk_mul_f32 v[28:29], v[10:11], v[16:17] op_sel:[0,1]
	s_waitcnt vmcnt(61)
	global_store_short v[148:149], v5, off offset:256
	v_cvt_pk_bf16_f32 v5, v17, s0
	v_pk_fma_f32 v[30:31], v[6:7], v[16:17], v[28:29] neg_lo:[0,0,1] neg_hi:[0,0,1]
	v_pk_fma_f32 v[16:17], v[6:7], v[16:17], v[28:29] op_sel_hi:[1,0,1]
	global_store_short v[148:149], v5, off offset:384
	v_mov_b32_e32 v31, v17
	s_nop 0
	v_pk_add_f32 v[16:17], v[30:31], v[128:129]
	s_nop 0
	v_cvt_pk_bf16_f32 v5, v16, s0
	v_pk_mul_f32 v[28:29], v[10:11], v[16:17] op_sel:[0,1]
	s_waitcnt vmcnt(61)
	global_store_short v[148:149], v5, off offset:1536
	v_cvt_pk_bf16_f32 v5, v17, s0
	v_pk_fma_f32 v[30:31], v[6:7], v[16:17], v[28:29] neg_lo:[0,0,1] neg_hi:[0,0,1]
	v_pk_fma_f32 v[16:17], v[6:7], v[16:17], v[28:29] op_sel_hi:[1,0,1]
	global_store_short v[148:149], v5, off offset:1664
	v_mov_b32_e32 v31, v17
	s_nop 0
	v_pk_add_f32 v[16:17], v[30:31], v[130:131]
	s_nop 0
	v_cvt_pk_bf16_f32 v5, v16, s0
	v_pk_mul_f32 v[28:29], v[10:11], v[16:17] op_sel:[0,1]
	s_waitcnt vmcnt(61)
	global_store_short v[148:149], v5, off offset:2816
	v_cvt_pk_bf16_f32 v5, v17, s0
	v_pk_fma_f32 v[30:31], v[6:7], v[16:17], v[28:29] neg_lo:[0,0,1] neg_hi:[0,0,1]
	v_pk_fma_f32 v[16:17], v[6:7], v[16:17], v[28:29] op_sel_hi:[1,0,1]
	global_store_short v[148:149], v5, off offset:2944
	v_mov_b32_e32 v31, v17
	s_nop 0
	v_pk_add_f32 v[16:17], v[30:31], v[132:133]
	s_nop 0
	v_cvt_pk_bf16_f32 v5, v16, s0
	v_pk_mul_f32 v[28:29], v[10:11], v[16:17] op_sel:[0,1]
	s_waitcnt vmcnt(61)
	global_store_short v[150:151], v5, off
	v_cvt_pk_bf16_f32 v5, v17, s0
	v_pk_fma_f32 v[30:31], v[6:7], v[16:17], v[28:29] neg_lo:[0,0,1] neg_hi:[0,0,1]
	v_pk_fma_f32 v[16:17], v[6:7], v[16:17], v[28:29] op_sel_hi:[1,0,1]
	global_store_short v[150:151], v5, off offset:128
	v_mov_b32_e32 v31, v17
	s_nop 0
	v_pk_add_f32 v[16:17], v[30:31], v[134:135]
	s_nop 0
	v_cvt_pk_bf16_f32 v5, v16, s0
	v_pk_mul_f32 v[28:29], v[10:11], v[16:17] op_sel:[0,1]
	s_waitcnt vmcnt(61)
; DEVI int otid() { int t = threadIdx.x; asm volatile("" : "+v"(t)); return t; }
; DEVI int obid() { int t = blockIdx.x; asm volatile("" : "+s"(t)); return t; }
; DEVI u16 f2bf(float f) { return (u16)(cvt_pk(f, 0.f) & 0xffffu); }
; DEVI void s5_scan(const Params& p) {
;     ...
;     for (int e = obid() * 512 + otid(); e < 64 * 4 * 64; e += gridDim.x * 512) { const int pp = e & 63, b = (e >> 6) & 3, g = e >> 8;
;         const float ar = apow[(((size_t)g * 64 + pp) * 34 + 32) * 2], ai = apow[(((size_t)g * 64 + pp) * 34 + 32) * 2 + 1]; float rr = 0.f, ri = 0.f;
; #pragma unroll 16
;         for (int c = 0; c < 256; ++c) { const size_t row = (size_t)g * 1024 + b * 256 + c; const float er = send[row * 128 + pp], ei = send[row * 128 + 64 + pp];
;             ue[row * 640 + 512 + pp] = f2bf(rr); ue[row * 640 + 576 + pp] = f2bf(ri);
;             const float nr = ar * rr - ai * ri + er, ni = ar * ri + ai * rr + ei; rr = nr; ri = ni; } }
	global_store_short v[150:151], v5, off offset:1280
	v_cvt_pk_bf16_f32 v5, v17, s0
	v_pk_fma_f32 v[30:31], v[6:7], v[16:17], v[28:29] neg_lo:[0,0,1] neg_hi:[0,0,1]
	v_pk_fma_f32 v[16:17], v[6:7], v[16:17], v[28:29] op_sel_hi:[1,0,1]
	global_store_short v[150:151], v5, off offset:1408
	v_mov_b32_e32 v31, v17
	s_nop 0
	v_pk_add_f32 v[16:17], v[30:31], v[136:137]
	s_nop 0
	v_cvt_pk_bf16_f32 v5, v16, s0
	v_pk_mul_f32 v[28:29], v[10:11], v[16:17] op_sel:[0,1]
	s_waitcnt vmcnt(61)
	global_store_short v[150:151], v5, off offset:2560
	v_cvt_pk_bf16_f32 v5, v17, s0
	v_pk_fma_f32 v[30:31], v[6:7], v[16:17], v[28:29] neg_lo:[0,0,1] neg_hi:[0,0,1]
	v_pk_fma_f32 v[16:17], v[6:7], v[16:17], v[28:29] op_sel_hi:[1,0,1]
	global_store_short v[150:151], v5, off offset:2688
	v_mov_b32_e32 v31, v17
	s_nop 0
	v_pk_add_f32 v[16:17], v[30:31], v[138:139]
	s_nop 0
	v_cvt_pk_bf16_f32 v5, v16, s0
	v_pk_mul_f32 v[28:29], v[10:11], v[16:17] op_sel:[0,1]
	s_waitcnt vmcnt(61)
	global_store_short v[150:151], v5, off offset:3840
	v_cvt_pk_bf16_f32 v5, v17, s0
	v_pk_fma_f32 v[30:31], v[6:7], v[16:17], v[28:29] neg_lo:[0,0,1] neg_hi:[0,0,1]
	v_pk_fma_f32 v[16:17], v[6:7], v[16:17], v[28:29] op_sel_hi:[1,0,1]
	global_store_short v[150:151], v5, off offset:3968
	v_mov_b32_e32 v31, v17
	s_nop 0
	v_pk_add_f32 v[16:17], v[30:31], v[140:141]
	s_nop 0
	s_add_i32 s6, s6, -32
	s_waitcnt vmcnt(30)
	s_cmp_eq_u32 s6, 0
	s_cbranch_scc1 .Ls5s_nopf
	v_lshl_add_u64 v[20:21], s[20:21], 0, v[14:15]
	v_add_co_u32_e32 v22, vcc, 0x12380000, v20
	s_nop 1
	v_addc_co_u32_e32 v23, vcc, 0, v21, vcc
	s_mov_b32 s0, 0x12381000
	v_add_co_u32_e32 v20, vcc, s0, v20
	s_nop 1
	v_addc_co_u32_e32 v21, vcc, 0, v21, vcc
	global_load_dword v60, v[22:23], off
	global_load_dword v61, v[22:23], off offset:256
	global_load_dword v62, v[22:23], off offset:512
	global_load_dword v63, v[22:23], off offset:768
	global_load_dword v64, v[22:23], off offset:1024
	global_load_dword v65, v[22:23], off offset:1280
	global_load_dword v66, v[22:23], off offset:1536
	global_load_dword v67, v[22:23], off offset:1792
	global_load_dword v68, v[22:23], off offset:2048
	global_load_dword v69, v[22:23], off offset:2304
	global_load_dword v70, v[22:23], off offset:2560
	global_load_dword v71, v[22:23], off offset:2816
	global_load_dword v72, v[22:23], off offset:3072
	global_load_dword v73, v[22:23], off offset:3328
	global_load_dword v74, v[22:23], off offset:3584
	global_load_dword v75, v[22:23], off offset:3840
	global_load_dword v126, v[20:21], off
	global_load_dword v127, v[20:21], off offset:256
	global_load_dword v128, v[20:21], off offset:512
	global_load_dword v129, v[20:21], off offset:768
	global_load_dword v130, v[20:21], off offset:1024
	global_load_dword v131, v[20:21], off offset:1280
	global_load_dword v132, v[20:21], off offset:1536
	global_load_dword v133, v[20:21], off offset:1792
	global_load_dword v134, v[20:21], off offset:2048
	global_load_dword v135, v[20:21], off offset:2304
	global_load_dword v136, v[20:21], off offset:2560
	global_load_dword v137, v[20:21], off offset:2816
	global_load_dword v138, v[20:21], off offset:3072
	global_load_dword v139, v[20:21], off offset:3328
	global_load_dword v140, v[20:21], off offset:3584
	global_load_dword v141, v[20:21], off offset:3840
	v_lshl_add_u64 v[14:15], v[14:15], 0, s[74:75]
.Ls5s_nopf:
	v_lshl_add_u64 v[18:19], s[20:21], 0, v[12:13]
	s_mov_b32 s0, 0xd380000
	v_add_co_u32_e32 v142, vcc, s0, v18
	s_nop 1
	v_addc_co_u32_e32 v143, vcc, 0, v19, vcc
	s_mov_b32 s0, 0xd381000
	v_add_co_u32_e32 v144, vcc, s0, v18
	s_nop 1
	v_addc_co_u32_e32 v145, vcc, 0, v19, vcc
	s_mov_b32 s0, 0xd382000
	v_add_co_u32_e32 v146, vcc, s0, v18
	s_nop 1
	v_addc_co_u32_e32 v147, vcc, 0, v19, vcc
	s_mov_b32 s0, 0xd383000
	v_add_co_u32_e32 v148, vcc, s0, v18
	s_nop 1
	v_addc_co_u32_e32 v149, vcc, 0, v19, vcc
	s_mov_b32 s0, 0xd384000
	v_add_co_u32_e32 v150, vcc, s0, v18
	s_nop 1
	v_addc_co_u32_e32 v151, vcc, 0, v19, vcc
	s_mov_b64 s[0:1], 0x5000
	v_lshl_add_u64 v[12:13], v[12:13], 0, s[0:1]
	v_cvt_pk_bf16_f32 v5, v16, s0
	v_pk_mul_f32 v[28:29], v[10:11], v[16:17] op_sel:[0,1]
	s_waitcnt vmcnt(61)
	global_store_short v[142:143], v5, off offset:1024
	v_cvt_pk_bf16_f32 v5, v17, s0
	v_pk_fma_f32 v[30:31], v[6:7], v[16:17], v[28:29] neg_lo:[0,0,1] neg_hi:[0,0,1]
	v_pk_fma_f32 v[16:17], v[6:7], v[16:17], v[28:29] op_sel_hi:[1,0,1]
	global_store_short v[142:143], v5, off offset:1152
	v_mov_b32_e32 v31, v17
	s_nop 0
	v_pk_add_f32 v[16:17], v[30:31], v[214:215]
	s_nop 0
	v_cvt_pk_bf16_f32 v5, v16, s0
	v_pk_mul_f32 v[28:29], v[10:11], v[16:17] op_sel:[0,1]
	s_waitcnt vmcnt(61)
	global_store_short v[142:143], v5, off offset:2304
	v_cvt_pk_bf16_f32 v5, v17, s0
	v_pk_fma_f32 v[30:31], v[6:7], v[16:17], v[28:29] neg_lo:[0,0,1] neg_hi:[0,0,1]
	v_pk_fma_f32 v[16:17], v[6:7], v[16:17], v[28:29] op_sel_hi:[1,0,1]
	global_store_short v[142:143], v5, off offset:2432
	v_mov_b32_e32 v31, v17
	s_nop 0
	v_pk_add_f32 v[16:17], v[30:31], v[216:217]
	s_nop 0
	v_cvt_pk_bf16_f32 v5, v16, s0
	v_pk_mul_f32 v[28:29], v[10:11], v[16:17] op_sel:[0,1]
	s_waitcnt vmcnt(61)
	global_store_short v[142:143], v5, off offset:3584
	v_cvt_pk_bf16_f32 v5, v17, s0
	v_pk_fma_f32 v[30:31], v[6:7], v[16:17], v[28:29] neg_lo:[0,0,1] neg_hi:[0,0,1]
	v_pk_fma_f32 v[16:17], v[6:7], v[16:17], v[28:29] op_sel_hi:[1,0,1]
	global_store_short v[142:143], v5, off offset:3712
	v_mov_b32_e32 v31, v17
	s_nop 0
	v_pk_add_f32 v[16:17], v[30:31], v[218:219]
	s_nop 0
	v_cvt_pk_bf16_f32 v5, v16, s0
	v_pk_mul_f32 v[28:29], v[10:11], v[16:17] op_sel:[0,1]
	s_waitcnt vmcnt(61)
; DEVI int otid() { int t = threadIdx.x; asm volatile("" : "+v"(t)); return t; }
; DEVI int obid() { int t = blockIdx.x; asm volatile("" : "+s"(t)); return t; }
; DEVI u16 f2bf(float f) { return (u16)(cvt_pk(f, 0.f) & 0xffffu); }
; DEVI void s5_scan(const Params& p) {
;     ...
;     for (int e = obid() * 512 + otid(); e < 64 * 4 * 64; e += gridDim.x * 512) { const int pp = e & 63, b = (e >> 6) & 3, g = e >> 8;
;         const float ar = apow[(((size_t)g * 64 + pp) * 34 + 32) * 2], ai = apow[(((size_t)g * 64 + pp) * 34 + 32) * 2 + 1]; float rr = 0.f, ri = 0.f;
; #pragma unroll 16
;         for (int c = 0; c < 256; ++c) { const size_t row = (size_t)g * 1024 + b * 256 + c; const float er = send[row * 128 + pp], ei = send[row * 128 + 64 + pp];
;             ue[row * 640 + 512 + pp] = f2bf(rr); ue[row * 640 + 576 + pp] = f2bf(ri);
;             const float nr = ar * rr - ai * ri + er, ni = ar * ri + ai * rr + ei; rr = nr; ri = ni; } }
	global_store_short v[144:145], v5, off offset:768
	v_cvt_pk_bf16_f32 v5, v17, s0
	v_pk_fma_f32 v[30:31], v[6:7], v[16:17], v[28:29] neg_lo:[0,0,1] neg_hi:[0,0,1]
	v_pk_fma_f32 v[16:17], v[6:7], v[16:17], v[28:29] op_sel_hi:[1,0,1]
	global_store_short v[144:145], v5, off offset:896
	v_mov_b32_e32 v31, v17
	s_nop 0
	v_pk_add_f32 v[16:17], v[30:31], v[220:221]
	s_nop 0
	v_cvt_pk_bf16_f32 v5, v16, s0
	v_pk_mul_f32 v[28:29], v[10:11], v[16:17] op_sel:[0,1]
	s_waitcnt vmcnt(61)
	global_store_short v[144:145], v5, off offset:2048
	v_cvt_pk_bf16_f32 v5, v17, s0
	v_pk_fma_f32 v[30:31], v[6:7], v[16:17], v[28:29] neg_lo:[0,0,1] neg_hi:[0,0,1]
	v_pk_fma_f32 v[16:17], v[6:7], v[16:17], v[28:29] op_sel_hi:[1,0,1]
	global_store_short v[144:145], v5, off offset:2176
	v_mov_b32_e32 v31, v17
	s_nop 0
	v_pk_add_f32 v[16:17], v[30:31], v[222:223]
	s_nop 0
	v_cvt_pk_bf16_f32 v5, v16, s0
	v_pk_mul_f32 v[28:29], v[10:11], v[16:17] op_sel:[0,1]
	s_waitcnt vmcnt(61)
	global_store_short v[144:145], v5, off offset:3328
	v_cvt_pk_bf16_f32 v5, v17, s0
	v_pk_fma_f32 v[30:31], v[6:7], v[16:17], v[28:29] neg_lo:[0,0,1] neg_hi:[0,0,1]
	v_pk_fma_f32 v[16:17], v[6:7], v[16:17], v[28:29] op_sel_hi:[1,0,1]
	global_store_short v[144:145], v5, off offset:3456
	v_mov_b32_e32 v31, v17
	s_nop 0
	v_pk_add_f32 v[16:17], v[30:31], v[224:225]
	s_nop 0
	v_cvt_pk_bf16_f32 v5, v16, s0
	v_pk_mul_f32 v[28:29], v[10:11], v[16:17] op_sel:[0,1]
	s_waitcnt vmcnt(61)
	global_store_short v[146:147], v5, off offset:512
	v_cvt_pk_bf16_f32 v5, v17, s0
	v_pk_fma_f32 v[30:31], v[6:7], v[16:17], v[28:29] neg_lo:[0,0,1] neg_hi:[0,0,1]
	v_pk_fma_f32 v[16:17], v[6:7], v[16:17], v[28:29] op_sel_hi:[1,0,1]
	global_store_short v[146:147], v5, off offset:640
	v_mov_b32_e32 v31, v17
	s_nop 0
	v_pk_add_f32 v[16:17], v[30:31], v[226:227]
	s_nop 0
	v_cvt_pk_bf16_f32 v5, v16, s0
	v_pk_mul_f32 v[28:29], v[10:11], v[16:17] op_sel:[0,1]
	s_waitcnt vmcnt(61)
	global_store_short v[146:147], v5, off offset:1792
	v_cvt_pk_bf16_f32 v5, v17, s0
	v_pk_fma_f32 v[30:31], v[6:7], v[16:17], v[28:29] neg_lo:[0,0,1] neg_hi:[0,0,1]
	v_pk_fma_f32 v[16:17], v[6:7], v[16:17], v[28:29] op_sel_hi:[1,0,1]
	global_store_short v[146:147], v5, off offset:1920
	v_mov_b32_e32 v31, v17
	s_nop 0
	v_pk_add_f32 v[16:17], v[30:31], v[228:229]
	s_nop 0
	v_cvt_pk_bf16_f32 v5, v16, s0
	v_pk_mul_f32 v[28:29], v[10:11], v[16:17] op_sel:[0,1]
	s_waitcnt vmcnt(61)
	global_store_short v[146:147], v5, off offset:3072
	v_cvt_pk_bf16_f32 v5, v17, s0
	v_pk_fma_f32 v[30:31], v[6:7], v[16:17], v[28:29] neg_lo:[0,0,1] neg_hi:[0,0,1]
	v_pk_fma_f32 v[16:17], v[6:7], v[16:17], v[28:29] op_sel_hi:[1,0,1]
	global_store_short v[146:147], v5, off offset:3200
	v_mov_b32_e32 v31, v17
	s_nop 0
	v_pk_add_f32 v[16:17], v[30:31], v[230:231]
	s_nop 0
	v_cvt_pk_bf16_f32 v5, v16, s0
	v_pk_mul_f32 v[28:29], v[10:11], v[16:17] op_sel:[0,1]
	s_waitcnt vmcnt(61)
	global_store_short v[148:149], v5, off offset:256
	v_cvt_pk_bf16_f32 v5, v17, s0
	v_pk_fma_f32 v[30:31], v[6:7], v[16:17], v[28:29] neg_lo:[0,0,1] neg_hi:[0,0,1]
	v_pk_fma_f32 v[16:17], v[6:7], v[16:17], v[28:29] op_sel_hi:[1,0,1]
	global_store_short v[148:149], v5, off offset:384
	v_mov_b32_e32 v31, v17
	s_nop 0
	v_pk_add_f32 v[16:17], v[30:31], v[232:233]
	s_nop 0
	v_cvt_pk_bf16_f32 v5, v16, s0
	v_pk_mul_f32 v[28:29], v[10:11], v[16:17] op_sel:[0,1]
	s_waitcnt vmcnt(61)
	global_store_short v[148:149], v5, off offset:1536
	v_cvt_pk_bf16_f32 v5, v17, s0
	v_pk_fma_f32 v[30:31], v[6:7], v[16:17], v[28:29] neg_lo:[0,0,1] neg_hi:[0,0,1]
	v_pk_fma_f32 v[16:17], v[6:7], v[16:17], v[28:29] op_sel_hi:[1,0,1]
	global_store_short v[148:149], v5, off offset:1664
	v_mov_b32_e32 v31, v17
	s_nop 0
	v_pk_add_f32 v[16:17], v[30:31], v[234:235]
	s_nop 0
	v_cvt_pk_bf16_f32 v5, v16, s0
	v_pk_mul_f32 v[28:29], v[10:11], v[16:17] op_sel:[0,1]
	s_waitcnt vmcnt(61)
	global_store_short v[148:149], v5, off offset:2816
	v_cvt_pk_bf16_f32 v5, v17, s0
	v_pk_fma_f32 v[30:31], v[6:7], v[16:17], v[28:29] neg_lo:[0,0,1] neg_hi:[0,0,1]
	v_pk_fma_f32 v[16:17], v[6:7], v[16:17], v[28:29] op_sel_hi:[1,0,1]
	global_store_short v[148:149], v5, off offset:2944
	v_mov_b32_e32 v31, v17
	s_nop 0
	v_pk_add_f32 v[16:17], v[30:31], v[236:237]
	s_nop 0
	v_cvt_pk_bf16_f32 v5, v16, s0
	v_pk_mul_f32 v[28:29], v[10:11], v[16:17] op_sel:[0,1]
	s_waitcnt vmcnt(61)
	global_store_short v[150:151], v5, off
	v_cvt_pk_bf16_f32 v5, v17, s0
	v_pk_fma_f32 v[30:31], v[6:7], v[16:17], v[28:29] neg_lo:[0,0,1] neg_hi:[0,0,1]
	v_pk_fma_f32 v[16:17], v[6:7], v[16:17], v[28:29] op_sel_hi:[1,0,1]
	global_store_short v[150:151], v5, off offset:128
	v_mov_b32_e32 v31, v17
	s_nop 0
	v_pk_add_f32 v[16:17], v[30:31], v[238:239]
	s_nop 0
	v_cvt_pk_bf16_f32 v5, v16, s0
	v_pk_mul_f32 v[28:29], v[10:11], v[16:17] op_sel:[0,1]
	s_waitcnt vmcnt(61)
	global_store_short v[150:151], v5, off offset:1280
	v_cvt_pk_bf16_f32 v5, v17, s0
	v_pk_fma_f32 v[30:31], v[6:7], v[16:17], v[28:29] neg_lo:[0,0,1] neg_hi:[0,0,1]
	v_pk_fma_f32 v[16:17], v[6:7], v[16:17], v[28:29] op_sel_hi:[1,0,1]
	global_store_short v[150:151], v5, off offset:1408
	v_mov_b32_e32 v31, v17
	s_nop 0
	v_pk_add_f32 v[16:17], v[30:31], v[244:245]
	s_nop 0
	v_cvt_pk_bf16_f32 v5, v16, s0
	v_pk_mul_f32 v[28:29], v[10:11], v[16:17] op_sel:[0,1]
	s_waitcnt vmcnt(61)
	global_store_short v[150:151], v5, off offset:2560
	v_cvt_pk_bf16_f32 v5, v17, s0
	v_pk_fma_f32 v[30:31], v[6:7], v[16:17], v[28:29] neg_lo:[0,0,1] neg_hi:[0,0,1]
	v_pk_fma_f32 v[16:17], v[6:7], v[16:17], v[28:29] op_sel_hi:[1,0,1]
	global_store_short v[150:151], v5, off offset:2688
	v_mov_b32_e32 v31, v17
	s_nop 0
	v_pk_add_f32 v[16:17], v[30:31], v[246:247]
	s_nop 0
	v_cvt_pk_bf16_f32 v5, v16, s0
	v_pk_mul_f32 v[28:29], v[10:11], v[16:17] op_sel:[0,1]
	s_waitcnt vmcnt(61)
	global_store_short v[150:151], v5, off offset:3840
	v_cvt_pk_bf16_f32 v5, v17, s0
	v_pk_fma_f32 v[30:31], v[6:7], v[16:17], v[28:29] neg_lo:[0,0,1] neg_hi:[0,0,1]
	v_pk_fma_f32 v[16:17], v[6:7], v[16:17], v[28:29] op_sel_hi:[1,0,1]
	global_store_short v[150:151], v5, off offset:3968
	v_mov_b32_e32 v31, v17
	s_nop 0
	v_pk_add_f32 v[16:17], v[30:31], v[248:249]
	s_nop 0
	s_cmp_eq_u32 s6, 0
	s_cbranch_scc0 .LBB0_1185
	v_add_u32_e32 v1, s40, v1
	s_movk_i32 s0, 0x3fff
	v_cmp_lt_i32_e32 vcc, s0, v1
	v_readlane_b32 s0, v253, 52
	s_or_b64 s[4:5], vcc, s[4:5]
	s_nop 0
	v_add_u32_e32 v3, s0, v3
	s_andn2_b64 exec, exec, s[4:5]
	s_cbranch_execnz .LBB0_1184
; DEVI int obid() { int t = blockIdx.x; asm volatile("" : "+s"(t)); return t; }
; DEVI size_t gemm_offB(const Gemm& g, const Unit& u) { return (g.split ? (size_t)(u.b >> 2) * g.sB + (size_t)(u.b & 3) * g.sB_lo : (size_t)u.b * g.sB) + (size_t)(u.pm >> g.pmsh) * g.sBpm; }
; DEVI bool unit_next(const Gemm& g, int i, Unit& u) {
;     const int nwg = g.nM * g.nN; int cc = obid() - g.wg_off; if (cc < 0) cc += gridDim.x; const long L = (long)i * gridDim.x + cc;
;     if (L >= (long)nwg * g.nB) return false;
;     u.b = (int)(L / nwg); int wgid = (int)(L % nwg);
;     { const int q = nwg / NXCD, r = nwg % NXCD, xcd = wgid % NXCD, off = wgid / NXCD; wgid = (xcd < r ? xcd * (q + 1) : r * (q + 1) + (xcd - r) * q) + off; }
;     const int nig = WGM * g.nN, gid = wgid / nig, fm = gid * WGM, gsz = (g.nM - fm) < WGM ? (g.nM - fm) : WGM;
;     u.pm = fm + ((wgid % nig) % gsz); u.pn = (wgid % nig) / gsz; return true;
; template <class Epi>
; DEVI void gemm_phase(LAS unsigned char* lds, const Gemm g, const Epi& E) {
;     ...
;     for (int i = 0; i < 2; ++i) { int R, C; stage_rc(tid * 16 + i * 8192, R, C); voffA[i] = (unsigned)(R * g.lda + C) * 2u; const int Rb = Epi::PERM ? ((R & ~31) + perm32(R & 31)) : R; voffB[i] = (unsigned)(Rb * g.ldb + C) * 2u; }
;     const size_t kstep = (size_t)(BK * 2);
;     const size_t hstepA = (size_t)HALF * g.lda * 2, hstepB = (size_t)HALF * g.ldb * 2;
;     const size_t tstepA = 2 * hstepA, tstepB = 2 * hstepB;
;     const unsigned ldsw = (unsigned)wid * 1024u;
;     const int aoff = lds_byte(wr * 64 + fr, fq * 8), boff = lds_byte(wc * 32 + fr, fq * 8);
;     ...
;     Unit cur, nxt; int ui = 0;
;     if (!unit_next(g, 0, cur)) return;
;     f32x4 acc[2][2][4][2];
; #pragma unroll
;     for (int a = 0; a < 2; ++a)
; #pragma unroll
;         for (int b = 0; b < 2; ++b)
; #pragma unroll
;             for (int m = 0; m < 4; ++m)
; #pragma unroll
;                 for (int n = 0; n < 2; ++n) acc[a][b][m][n] = (f32x4){0.f, 0.f, 0.f, 0.f};
;     bf16x8 At[4][2], B0[2][2], B1[2][2];
;     const char* cA = (const char*)g.A + gemm_offA(g, cur) * 2 + (size_t)cur.pm * tstepA;
;     const char* cB = (const char*)g.Bt + gemm_offB(g, cur) * 2 + (size_t)cur.pn * tstepB;
;     PG8_STAGE(PG8_SB(0, 0), cB, voffB); PG8_STAGE(PG8_SA(0, 0), cA, voffA); PG8_STAGE(PG8_SB(0, 1), cB + hstepB, voffB); PG8_STAGE(PG8_SA(0, 1), cA + hstepA, voffA);
;     if (wr == 1) PG8_BAR;
.LBB0_1187:
	s_or_b64 exec, exec, s[2:3]
	v_readlane_b32 s0, v254, 2
	s_lshl_b32 s18, s0, 21
	v_mov_b32_e32 v10, v154
	s_sub_i32 s0, s33, 64
	s_ashr_i32 s1, s0, 31
	s_and_b32 s4, s1, s22
	s_add_i32 s4, s4, s0
	s_cmp_gt_i32 s4, 63
	v_readfirstlane_b32 s19, v10
	s_cbranch_scc1 .LBB0_1203
	v_lshlrev_b32_e32 v0, 4, v10
	v_add_u32_e32 v1, 0x2000, v0
	v_ashrrev_i32_e32 v2, 31, v1
	v_lshrrev_b32_e32 v2, 22, v2
	v_add_u32_e32 v2, v1, v2
	v_ashrrev_i32_e32 v2, 10, v2
	v_mul_i32_i24_e32 v4, 0x400, v2
	v_sub_u32_e32 v1, v1, v4
	v_lshrrev_b32_e32 v4, 4, v1
	v_bitop3_b32 v1, v4, v1, 32 bitop3:0x6c
	v_ashrrev_i32_e32 v4, 31, v1
	v_lshrrev_b32_e32 v4, 26, v4
	v_add_u32_e32 v4, v1, v4
	v_ashrrev_i32_e32 v5, 6, v4
	v_and_b32_e32 v4, 0xc0, v4
	v_sub_u32_e32 v1, v1, v4
	v_lshlrev_b32_e32 v3, 5, v2
	v_ashrrev_i16_sdwa v1, v161, sext(v1) dst_sel:DWORD dst_unused:UNUSED_PAD src0_sel:DWORD src1_sel:BYTE_0
	v_lshlrev_b32_e32 v2, 3, v2
	v_and_b32_e32 v3, 32, v3
	v_bfe_i32 v1, v1, 0, 16
	v_and_b32_e32 v2, -16, v2
	v_add_u32_e32 v2, v5, v2
	v_add_lshl_u32 v1, v3, v1, 1
	v_bfe_i32 v3, v10, 27, 1
	v_and_b32_e32 v4, 3, v5
	s_mov_b32 s5, 0x1fffe0
	v_lshrrev_b32_e32 v5, 2, v2
	v_lshlrev_b32_e32 v6, 1, v2
	v_lshrrev_b32_e32 v3, 22, v3
	v_and_or_b32 v4, v2, s5, v4
	v_and_b32_e32 v5, 4, v5
	v_and_b32_e32 v6, 24, v6
	v_add_u32_e32 v3, v0, v3
	v_or3_b32 v4, v4, v5, v6
	v_and_b32_e32 v3, 0xfffffc00, v3
	v_lshl_add_u32 v130, v4, 11, v1
	v_lshl_add_u32 v132, v2, 11, v1
	v_ashrrev_i32_e32 v1, 31, v10
	v_sub_u32_e32 v0, v0, v3
	v_lshrrev_b32_e32 v1, 26, v1
	v_lshrrev_b32_e32 v3, 4, v0
	v_add_u32_e32 v1, v10, v1
	v_bitop3_b32 v3, v3, v0, 32 bitop3:0x6c
	v_ashrrev_i32_e32 v0, 31, v0
	v_readlane_b32 s0, v252, 36
	v_ashrrev_i32_e32 v1, 6, v1
	v_lshrrev_b32_e32 v0, 26, v0
	s_add_u32 s26, s0, s18
	v_readlane_b32 s0, v252, 37
	v_lshlrev_b32_e32 v2, 5, v1
	v_add_u32_e32 v0, v3, v0
	v_lshlrev_b32_e32 v1, 3, v1
	s_addc_u32 s0, s0, 0
	v_readlane_b32 s1, v252, 10
	v_ashrrev_i32_e32 v0, 6, v0
	v_and_b32_e32 v1, -16, v1
	s_add_u32 s1, s1, s18
	v_readlane_b32 s2, v252, 11
	v_mul_i32_i24_e32 v4, 64, v0
	v_add_u32_e32 v1, v0, v1
	v_and_b32_e32 v0, 3, v0
	s_addc_u32 s27, s2, 0
	v_and_or_b32 v0, v1, s5, v0
	s_ashr_i32 s5, s4, 31
	s_lshr_b32 s5, s5, 30
	s_add_i32 s5, s4, s5
	s_and_b32 s6, s5, -4
	s_ashr_i32 s45, s5, 2
	s_sub_i32 s4, s4, s6
	s_ashr_i32 s6, s5, 4
	s_ashr_i32 s2, s19, 6
	s_ashr_i32 s7, s6, 31
	s_lshl_b32 s5, s45, 9
	s_ashr_i32 s3, s19, 8
	s_lshl_b32 s38, s2, 10
	s_and_b32 s5, s5, 0x600
	s_lshl_b64 s[6:7], s[6:7], 19
	s_add_u32 s6, s26, s6
	s_addc_u32 s7, s0, s7
	s_add_u32 s6, s6, s5
	s_addc_u32 s7, s7, 0
	s_add_u32 s10, s1, s5
	v_sub_u32_e32 v3, v3, v4
	s_addc_u32 s11, s27, 0
	s_ashr_i32 s5, s4, 31
	v_ashrrev_i16_sdwa v3, v161, sext(v3) dst_sel:DWORD dst_unused:UNUSED_PAD src0_sel:DWORD src1_sel:BYTE_0
	v_lshrrev_b32_e32 v4, 2, v1
	v_lshlrev_b32_e32 v5, 1, v1
	s_lshl_b64 s[8:9], s[4:5], 19
	v_and_b32_e32 v2, 32, v2
	v_bfe_i32 v3, v3, 0, 16
	v_and_b32_e32 v4, 4, v4
	v_and_b32_e32 v5, 24, v5
	s_add_u32 s8, s10, s8
	v_or3_b32 v0, v0, v4, v5
	v_add_lshl_u32 v2, v2, v3, 1
	s_addc_u32 s9, s11, s9
	s_add_i32 s39, s38, 0
	v_lshl_add_u32 v8, v0, 11, v2
	s_add_i32 m0, s39, 0x10000
	v_lshl_add_u32 v134, v1, 11, v2
	global_load_lds_dwordx4 v8, s[8:9]
	s_add_i32 m0, s39, 0x12000
	s_add_i32 s40, s39, 0x2000
	global_load_lds_dwordx4 v130, s[8:9]
	s_mov_b32 m0, s39
	s_add_u32 s10, s8, 0x40000
	global_load_lds_dwordx4 v134, s[6:7]
	s_mov_b32 m0, s40
	s_addc_u32 s11, s9, 0
	global_load_lds_dwordx4 v132, s[6:7]
	s_add_i32 m0, s39, 0x14000
	v_mov_b32_e32 v131, v9
	global_load_lds_dwordx4 v8, s[10:11]
	s_add_i32 m0, s39, 0x16000
	v_mov_b32_e32 v135, v9
	global_load_lds_dwordx4 v130, s[10:11]
	s_add_u32 s10, s6, 0x40000
	s_addc_u32 s11, s7, 0
	s_add_i32 s41, s39, 0x4000
	s_mov_b32 m0, s41
	s_add_i32 s42, s39, 0x6000
	global_load_lds_dwordx4 v134, s[10:11]
	s_mov_b32 m0, s42
	v_mov_b32_e32 v133, v9
	global_load_lds_dwordx4 v132, s[10:11]
	v_lshl_add_u64 v[6:7], s[8:9], 0, v[8:9]
	v_lshl_add_u64 v[4:5], s[8:9], 0, v[130:131]
	v_lshl_add_u64 v[2:3], s[6:7], 0, v[134:135]
	s_cmp_lg_u32 s3, 1
	v_lshl_add_u64 v[0:1], s[6:7], 0, v[132:133]
	s_cbranch_scc1 .LBB0_1190
	s_barrier

; DEVI int obid() { int t = blockIdx.x; asm volatile("" : "+s"(t)); return t; }
; DEVI bool unit_next(const Gemm& g, int i, Unit& u) {
;     const int nwg = g.nM * g.nN; int cc = obid() - g.wg_off; if (cc < 0) cc += gridDim.x; const long L = (long)i * gridDim.x + cc;
;     if (L >= (long)nwg * g.nB) return false;
;     u.b = (int)(L / nwg); int wgid = (int)(L % nwg);
;     { const int q = nwg / NXCD, r = nwg % NXCD, xcd = wgid % NXCD, off = wgid / NXCD; wgid = (xcd < r ? xcd * (q + 1) : r * (q + 1) + (xcd - r) * q) + off; }
;     const int nig = WGM * g.nN, gid = wgid / nig, fm = gid * WGM, gsz = (g.nM - fm) < WGM ? (g.nM - fm) : WGM;
;     u.pm = fm + ((wgid % nig) % gsz); u.pn = (wgid % nig) / gsz; return true;
.LBB0_1191:
	s_sub_i32 s2, s33, 64
	s_ashr_i32 s3, s2, 31
	s_and_b32 s3, s3, s22
	s_add_i32 s48, s48, 1
	s_add_i32 s3, s3, s2
	s_mul_i32 s2, s48, s22
	s_ashr_i32 s11, s3, 31
	s_mul_hi_u32 s5, s48, s22
	s_add_u32 s2, s2, s3
	s_addc_u32 s3, s5, s11
	v_cmp_gt_i64_e64 s[14:15], s[2:3], 63
	v_cmp_lt_i64_e64 s[16:17], s[2:3], 64
	s_and_b64 vcc, exec, s[14:15]
	s_cbranch_vccnz .LBB0_1193
	s_ashr_i32 s5, s3, 31
	s_lshr_b32 s5, s5, 30
	s_add_u32 s10, s2, s5
	s_addc_u32 s11, s3, 0
	s_lshr_b64 s[10:11], s[10:11], 2
	s_lshl_b32 s3, s10, 2
	s_sub_i32 s12, s2, s3
